# in-proj0 idle-round weight prep: the transposes' LDS reads issued eight at a time instead of one exposed round trip per read
# speedup vs baseline: 1.0092x; 1.0006x over previous
; #define LAS __attribute__((address_space(3)))
; __device__ __forceinline__ unsigned pk2(float lo, float hi) { return pg8::cvt_pk_bf16(lo, hi); }
; template <bool GATEMAP = false>
; __device__ __forceinline__ void p0_transpose_item(const float* W, int N, bf16* WT, int ldwt, int koff, const float* gain, LAS float* scr, int item, int lane) {
;     const int nblk = N / 64, kb = item / nblk, nb = item % nblk, k0 = 64 * kb, n0 = 64 * nb; const int nd0 = GATEMAP ? gate_row(n0) : n0;
;     const int ks = lane >> 4, n4 = (lane & 15) * 4;
;     f32x4 v[16];
; #pragma unroll
;     for (int i = 0; i < 16; ++i) v[i] = *(const f32x4*)(W + (size_t)(k0 + 4 * i + ks) * N + n0 + n4);
;     if (gain) {
; #pragma unroll
;         for (int i = 0; i < 16; ++i) v[i] = v[i] * gain[k0 + 4 * i + ks];
;     }
; #pragma unroll
;     for (int i = 0; i < 16; ++i) { LAS float* d = scr + (4 * i + ks) * 65 + n4; d[0] = v[i][0]; d[1] = v[i][1]; d[2] = v[i][2]; d[3] = v[i][3]; }
;     asm volatile("s_waitcnt lgkmcnt(0)" ::: "memory");
;     const int c = lane & 7;
; #pragma unroll
;     for (int j = 0; j < 8; ++j) { const int n = (lane >> 3) + 8 * j; const LAS float* q = scr + (8 * c) * 65 + n;
;         v4u o; o.x = pk2(q[0 * 65], q[1 * 65]); o.y = pk2(q[2 * 65], q[3 * 65]); o.z = pk2(q[4 * 65], q[5 * 65]); o.w = pk2(q[6 * 65], q[7 * 65]);
;         *(v4u*)(WT + (size_t)(nd0 + n) * ldwt + koff + k0 + 8 * c) = o; }
;     asm volatile("s_waitcnt lgkmcnt(0)" ::: "memory");
; }
; template <int PART>
; __device__ __forceinline__ void phase_prologue_late(const Params& p, LAS unsigned char* lds, int cu0) {
;     ...
;         for (int it = gw; it < 16 * 16 + I_W1 + I_IN1 + I_OUT1; it += NGW) {
;             int r = it;
;             if (r < 16 * 16) { p0_transpose_item(p.in[13], D, (bf16*)(ws + WS_WOUT0), D, 0, nullptr, scr, r, lane); continue; } r -= 16 * 16;
;             if (r < I_W1) { p0_transpose_item(p.in[22], FF, (bf16*)(ws + WS_W1_0), D, 0, p.in[6], scr, r, lane); continue; } r -= I_W1;
;             if (r < I_IN1) { p0_transpose_item(p.in[14], NZ1, (bf16*)(ws + WS_WIN1), D, 0, p.in[5] + D, scr, r, lane); continue; } r -= I_IN1;
;             p0_transpose_item(p.in[21] + (size_t)512 * D, D, (bf16*)(ws + WS_WOUT1), D, 512, nullptr, scr, r, lane);
.LBB0_164:
	s_cmpk_gt_i32 s8, 0xff
	s_mov_b64 s[6:7], -1
	s_cbranch_scc0 .LBB0_176
	s_cmpk_gt_u32 s8, 0x4ff
	s_cbranch_scc0 .LBB0_171
	s_cmpk_gt_u32 s8, 0x67f
	s_cbranch_scc0 .LBB0_168
	s_and_b32 s7, s53, 0x3c0
	s_and_b32 s6, s29, 0x3c0
	v_bitop3_b32 v2, s7, v82, v118 bitop3:0xde
	s_lshl_b32 s0, s6, 2
	v_lshl_add_u64 v[0:1], v[80:81], 0, s[0:1]
	v_lshlrev_b32_e32 v64, 12, v2
	v_lshl_add_u64 v[60:61], v[0:1], 0, v[64:65]
	v_add_co_u32_e32 v4, vcc, 0x4000, v60
	s_xor_b32 s0, s7, 0x200
	s_nop 0
	v_addc_co_u32_e32 v5, vcc, 0, v61, vcc
	v_add_co_u32_e32 v8, vcc, 0x8000, v60
	global_load_dwordx4 v[0:3], v[60:61], off
	s_nop 0
	global_load_dwordx4 v[4:7], v[4:5], off
	v_addc_co_u32_e32 v9, vcc, 0, v61, vcc
	v_add_co_u32_e32 v12, vcc, 0xc000, v60
	s_lshl_b32 s0, s0, 1
	s_nop 0
	v_addc_co_u32_e32 v13, vcc, 0, v61, vcc
	v_add_co_u32_e32 v16, vcc, 0x10000, v60
	global_load_dwordx4 v[8:11], v[8:9], off
	s_nop 0
	global_load_dwordx4 v[12:15], v[12:13], off
	v_addc_co_u32_e32 v17, vcc, 0, v61, vcc
	v_add_co_u32_e32 v20, vcc, 0x14000, v60
	s_nop 1
	v_addc_co_u32_e32 v21, vcc, 0, v61, vcc
	v_add_co_u32_e32 v24, vcc, 0x18000, v60
	global_load_dwordx4 v[16:19], v[16:17], off
	s_nop 0
	global_load_dwordx4 v[20:23], v[20:21], off
	v_addc_co_u32_e32 v25, vcc, 0, v61, vcc
	v_add_co_u32_e32 v28, vcc, 0x1c000, v60
	s_nop 1
	v_addc_co_u32_e32 v29, vcc, 0, v61, vcc
	v_add_co_u32_e32 v32, vcc, 0x20000, v60
	global_load_dwordx4 v[24:27], v[24:25], off
	s_nop 0
	global_load_dwordx4 v[28:31], v[28:29], off
	v_addc_co_u32_e32 v33, vcc, 0, v61, vcc
	v_add_co_u32_e32 v36, vcc, 0x24000, v60
	s_nop 1
	v_addc_co_u32_e32 v37, vcc, 0, v61, vcc
	v_add_co_u32_e32 v40, vcc, 0x28000, v60
	global_load_dwordx4 v[32:35], v[32:33], off
	s_nop 0
	global_load_dwordx4 v[36:39], v[36:37], off
	v_addc_co_u32_e32 v41, vcc, 0, v61, vcc
	v_add_co_u32_e32 v44, vcc, 0x2c000, v60
	s_nop 1
	v_addc_co_u32_e32 v45, vcc, 0, v61, vcc
	v_add_co_u32_e32 v48, vcc, 0x30000, v60
	global_load_dwordx4 v[40:43], v[40:41], off
	s_nop 0
	global_load_dwordx4 v[44:47], v[44:45], off
	v_addc_co_u32_e32 v49, vcc, 0, v61, vcc
	v_add_co_u32_e32 v52, vcc, 0x34000, v60
	s_nop 1
	v_addc_co_u32_e32 v53, vcc, 0, v61, vcc
	global_load_dwordx4 v[48:51], v[48:49], off
	s_nop 0
	global_load_dwordx4 v[52:55], v[52:53], off
	v_add_co_u32_e32 v56, vcc, 0x38000, v60
	s_nop 1
	v_addc_co_u32_e32 v57, vcc, 0, v61, vcc
	global_load_dwordx4 v[56:59], v[56:57], off
	v_add_co_u32_e32 v60, vcc, 0x3c000, v60
	s_nop 1
	v_addc_co_u32_e32 v61, vcc, 0, v61, vcc
	global_load_dwordx4 v[60:63], v[60:61], off
	s_waitcnt vmcnt(15)
	ds_write2_b32 v83, v0, v1 offset1:1
	ds_write2_b32 v83, v2, v3 offset0:2 offset1:3
	s_waitcnt vmcnt(14)
	ds_write2_b32 v93, v4, v5 offset1:1
	ds_write2_b32 v94, v6, v7 offset1:1
	s_waitcnt vmcnt(13)
	ds_write2_b32 v95, v8, v9 offset1:1
	ds_write2_b32 v96, v10, v11 offset1:1
	s_waitcnt vmcnt(12)
	ds_write2_b32 v97, v12, v13 offset1:1
	ds_write2_b32 v98, v14, v15 offset1:1
	s_waitcnt vmcnt(11)
	ds_write2_b32 v99, v16, v17 offset1:1
	ds_write2_b32 v100, v18, v19 offset1:1
	s_waitcnt vmcnt(10)
	ds_write2_b32 v101, v20, v21 offset1:1
	ds_write2_b32 v102, v22, v23 offset1:1
	s_waitcnt vmcnt(9)
	ds_write2_b32 v103, v24, v25 offset1:1
	ds_write2_b32 v104, v26, v27 offset1:1
	s_waitcnt vmcnt(8)
	ds_write2_b32 v105, v28, v29 offset1:1
	ds_write2_b32 v106, v30, v31 offset1:1
	s_waitcnt vmcnt(7)
	ds_write2_b32 v107, v32, v33 offset1:1
	ds_write2_b32 v108, v34, v35 offset1:1
	s_waitcnt vmcnt(6)
	ds_write2_b32 v109, v36, v37 offset1:1
	ds_write2_b32 v110, v38, v39 offset1:1
	s_waitcnt vmcnt(5)
	ds_write2_b32 v111, v40, v41 offset1:1
	ds_write2_b32 v112, v42, v43 offset1:1
	s_waitcnt vmcnt(4)
	ds_write2_b32 v113, v44, v45 offset1:1
	ds_write2_b32 v114, v46, v47 offset1:1
	s_waitcnt vmcnt(3)
	ds_write2_b32 v115, v48, v49 offset1:1
	ds_write2_b32 v116, v50, v51 offset1:1
	s_waitcnt vmcnt(2)
	ds_write2_b32 v117, v52, v53 offset1:1
	v_add_u32_e32 v0, 0x34d8, v83
	ds_write2_b32 v0, v54, v55 offset1:1
	v_add_u32_e32 v0, 0x38e0, v83
	v_add_u32_e32 v10, 0x400, v85
	v_or_b32_e32 v8, s6, v84
	s_waitcnt vmcnt(1)
	ds_write2_b32 v0, v56, v57 offset1:1
	v_add_u32_e32 v0, 0x38e8, v83
	ds_write2_b32 v0, v58, v59 offset1:1
	v_add_u32_e32 v0, 0x3cf0, v83
	v_lshl_add_u64 v[6:7], v[66:67], 0, s[0:1]
	v_lshlrev_b32_e32 v64, 11, v8
	s_waitcnt vmcnt(0)
	ds_write2_b32 v0, v60, v61 offset1:1
	v_add_u32_e32 v0, 0x3cf8, v83
	ds_write2_b32 v0, v62, v63 offset1:1
	s_waitcnt lgkmcnt(0)
	ds_read2_b32 v[150:151], v85 offset1:65
	ds_read2_b32 v[152:153], v85 offset0:130 offset1:195
	ds_read2_b32 v[154:155], v10 offset0:4 offset1:69
	ds_read2_b32 v[156:157], v10 offset0:134 offset1:199
	ds_read2_b32 v[158:159], v85 offset0:8 offset1:73
	ds_read2_b32 v[160:161], v85 offset0:138 offset1:203
	ds_read2_b32 v[162:163], v10 offset0:12 offset1:77
	ds_read2_b32 v[164:165], v10 offset0:142 offset1:207
	s_waitcnt lgkmcnt(7)
	v_cvt_pk_bf16_f32 v0, v150, v151
	s_waitcnt lgkmcnt(6)
	v_cvt_pk_bf16_f32 v1, v152, v153
	s_waitcnt lgkmcnt(5)
	v_cvt_pk_bf16_f32 v2, v154, v155
	s_waitcnt lgkmcnt(4)
	v_cvt_pk_bf16_f32 v3, v156, v157
	v_lshl_add_u64 v[8:9], v[6:7], 0, v[64:65]
	global_store_dwordx4 v[8:9], v[0:3], off
	v_or_b32_e32 v8, s6, v86
	v_lshlrev_b32_e32 v64, 11, v8
	s_waitcnt lgkmcnt(3)
	v_cvt_pk_bf16_f32 v0, v158, v159
	s_waitcnt lgkmcnt(2)
	v_cvt_pk_bf16_f32 v1, v160, v161
	s_waitcnt lgkmcnt(1)
	v_cvt_pk_bf16_f32 v2, v162, v163
	s_waitcnt lgkmcnt(0)
; #define LAS __attribute__((address_space(3)))
; __device__ __forceinline__ unsigned pk2(float lo, float hi) { return pg8::cvt_pk_bf16(lo, hi); }
; __host__ __device__ __forceinline__ int gate_row(int n) { if (n < 512) return n; const int base = n < 1536 ? 512 : 1536, q = n - base, h = q >> 9, t = (q & 511) >> 7, r = q & 127; return base + t * 256 + h * 128 + r; }
; template <bool GATEMAP = false>
; __device__ __forceinline__ void p0_transpose_item(const float* W, int N, bf16* WT, int ldwt, int koff, const float* gain, LAS float* scr, int item, int lane) {
;     const int nblk = N / 64, kb = item / nblk, nb = item % nblk, k0 = 64 * kb, n0 = 64 * nb; const int nd0 = GATEMAP ? gate_row(n0) : n0;
;     const int ks = lane >> 4, n4 = (lane & 15) * 4;
;     f32x4 v[16];
; #pragma unroll
;     for (int i = 0; i < 16; ++i) v[i] = *(const f32x4*)(W + (size_t)(k0 + 4 * i + ks) * N + n0 + n4);
;     if (gain) {
; #pragma unroll
;         for (int i = 0; i < 16; ++i) v[i] = v[i] * gain[k0 + 4 * i + ks];
;     }
; #pragma unroll
;     for (int i = 0; i < 16; ++i) { LAS float* d = scr + (4 * i + ks) * 65 + n4; d[0] = v[i][0]; d[1] = v[i][1]; d[2] = v[i][2]; d[3] = v[i][3]; }
;     asm volatile("s_waitcnt lgkmcnt(0)" ::: "memory");
;     const int c = lane & 7;
; #pragma unroll
;     for (int j = 0; j < 8; ++j) { const int n = (lane >> 3) + 8 * j; const LAS float* q = scr + (8 * c) * 65 + n;
;         v4u o; o.x = pk2(q[0 * 65], q[1 * 65]); o.y = pk2(q[2 * 65], q[3 * 65]); o.z = pk2(q[4 * 65], q[5 * 65]); o.w = pk2(q[6 * 65], q[7 * 65]);
;         *(v4u*)(WT + (size_t)(nd0 + n) * ldwt + koff + k0 + 8 * c) = o; }
;     asm volatile("s_waitcnt lgkmcnt(0)" ::: "memory");
; }
; template <int PART>
; __device__ __forceinline__ void phase_prologue_late(const Params& p, LAS unsigned char* lds, int cu0) {
;     ...
;         for (int it = gw; it < 16 * 16 + I_W1 + I_IN1 + I_OUT1; it += NGW) {
;             int r = it;
;             if (r < 16 * 16) { p0_transpose_item(p.in[13], D, (bf16*)(ws + WS_WOUT0), D, 0, nullptr, scr, r, lane); continue; } r -= 16 * 16;
;             if (r < I_W1) { p0_transpose_item(p.in[22], FF, (bf16*)(ws + WS_W1_0), D, 0, p.in[6], scr, r, lane); continue; } r -= I_W1;
;             if (r < I_IN1) { p0_transpose_item(p.in[14], NZ1, (bf16*)(ws + WS_WIN1), D, 0, p.in[5] + D, scr, r, lane); continue; } r -= I_IN1;
	v_cvt_pk_bf16_f32 v3, v164, v165
	v_lshl_add_u64 v[8:9], v[6:7], 0, v[64:65]
	global_store_dwordx4 v[8:9], v[0:3], off
	v_or_b32_e32 v8, s6, v87
	v_lshlrev_b32_e32 v64, 11, v8
	ds_read2_b32 v[150:151], v85 offset0:16 offset1:81
	ds_read2_b32 v[152:153], v85 offset0:146 offset1:211
	ds_read2_b32 v[154:155], v10 offset0:20 offset1:85
	ds_read2_b32 v[156:157], v10 offset0:150 offset1:215
	ds_read2_b32 v[158:159], v85 offset0:24 offset1:89
	ds_read2_b32 v[160:161], v85 offset0:154 offset1:219
	ds_read2_b32 v[162:163], v10 offset0:28 offset1:93
	ds_read2_b32 v[164:165], v10 offset0:158 offset1:223
	s_waitcnt lgkmcnt(7)
	v_cvt_pk_bf16_f32 v0, v150, v151
	s_waitcnt lgkmcnt(6)
	v_cvt_pk_bf16_f32 v1, v152, v153
	s_waitcnt lgkmcnt(5)
	v_cvt_pk_bf16_f32 v2, v154, v155
	s_waitcnt lgkmcnt(4)
	v_cvt_pk_bf16_f32 v3, v156, v157
	v_lshl_add_u64 v[8:9], v[6:7], 0, v[64:65]
	global_store_dwordx4 v[8:9], v[0:3], off
	v_or_b32_e32 v8, s6, v88
	v_lshlrev_b32_e32 v64, 11, v8
	s_waitcnt lgkmcnt(3)
	v_cvt_pk_bf16_f32 v0, v158, v159
	s_waitcnt lgkmcnt(2)
	v_cvt_pk_bf16_f32 v1, v160, v161
	s_waitcnt lgkmcnt(1)
	v_cvt_pk_bf16_f32 v2, v162, v163
	s_waitcnt lgkmcnt(0)
	v_cvt_pk_bf16_f32 v3, v164, v165
	v_lshl_add_u64 v[8:9], v[6:7], 0, v[64:65]
	global_store_dwordx4 v[8:9], v[0:3], off
	v_or_b32_e32 v8, s6, v89
	v_lshlrev_b32_e32 v64, 11, v8
	ds_read2_b32 v[150:151], v85 offset0:32 offset1:97
	ds_read2_b32 v[152:153], v85 offset0:162 offset1:227
	ds_read2_b32 v[154:155], v10 offset0:36 offset1:101
	ds_read2_b32 v[156:157], v10 offset0:166 offset1:231
	ds_read2_b32 v[158:159], v85 offset0:40 offset1:105
	ds_read2_b32 v[160:161], v85 offset0:170 offset1:235
	ds_read2_b32 v[162:163], v10 offset0:44 offset1:109
	ds_read2_b32 v[164:165], v10 offset0:174 offset1:239
	s_waitcnt lgkmcnt(7)
	v_cvt_pk_bf16_f32 v0, v150, v151
	s_waitcnt lgkmcnt(6)
	v_cvt_pk_bf16_f32 v1, v152, v153
	s_waitcnt lgkmcnt(5)
	v_cvt_pk_bf16_f32 v2, v154, v155
	s_waitcnt lgkmcnt(4)
	v_cvt_pk_bf16_f32 v3, v156, v157
	v_lshl_add_u64 v[8:9], v[6:7], 0, v[64:65]
	global_store_dwordx4 v[8:9], v[0:3], off
	v_or_b32_e32 v8, s6, v90
	v_lshlrev_b32_e32 v64, 11, v8
	s_waitcnt lgkmcnt(3)
	v_cvt_pk_bf16_f32 v0, v158, v159
	s_waitcnt lgkmcnt(2)
	v_cvt_pk_bf16_f32 v1, v160, v161
	s_waitcnt lgkmcnt(1)
	v_cvt_pk_bf16_f32 v2, v162, v163
	s_waitcnt lgkmcnt(0)
	v_cvt_pk_bf16_f32 v3, v164, v165
	v_lshl_add_u64 v[8:9], v[6:7], 0, v[64:65]
	global_store_dwordx4 v[8:9], v[0:3], off
	v_or_b32_e32 v8, s6, v91
	v_lshlrev_b32_e32 v64, 11, v8
	ds_read2_b32 v[150:151], v85 offset0:48 offset1:113
	ds_read2_b32 v[152:153], v85 offset0:178 offset1:243
	ds_read2_b32 v[154:155], v10 offset0:52 offset1:117
	ds_read2_b32 v[156:157], v10 offset0:182 offset1:247
	ds_read2_b32 v[158:159], v85 offset0:56 offset1:121
	ds_read2_b32 v[160:161], v85 offset0:186 offset1:251
	ds_read2_b32 v[162:163], v10 offset0:60 offset1:125
	ds_read2_b32 v[164:165], v10 offset0:190 offset1:255
	s_waitcnt lgkmcnt(7)
	v_cvt_pk_bf16_f32 v0, v150, v151
	s_waitcnt lgkmcnt(6)
	v_cvt_pk_bf16_f32 v1, v152, v153
	s_waitcnt lgkmcnt(5)
	v_cvt_pk_bf16_f32 v2, v154, v155
	s_waitcnt lgkmcnt(4)
	v_cvt_pk_bf16_f32 v3, v156, v157
	v_lshl_add_u64 v[8:9], v[6:7], 0, v[64:65]
	global_store_dwordx4 v[8:9], v[0:3], off
	s_waitcnt lgkmcnt(3)
	s_nop 0
	v_cvt_pk_bf16_f32 v0, v158, v159
	s_waitcnt lgkmcnt(2)
	v_cvt_pk_bf16_f32 v1, v160, v161
	s_waitcnt lgkmcnt(1)
	v_cvt_pk_bf16_f32 v2, v162, v163
	v_or_b32_e32 v3, s6, v92
	v_lshlrev_b32_e32 v64, 11, v3
	s_waitcnt lgkmcnt(0)
	v_cvt_pk_bf16_f32 v3, v164, v165
	v_lshl_add_u64 v[4:5], v[6:7], 0, v[64:65]
	global_store_dwordx4 v[4:5], v[0:3], off
	s_waitcnt lgkmcnt(0)
	s_mov_b64 s[6:7], 0
.LBB0_168:
	s_andn2_b64 vcc, exec, s[6:7]
	s_cbranch_vccnz .LBB0_170
	s_add_i32 s0, s8, 0xfb00
	s_and_b32 s6, s0, 0xffff
	s_mul_i32 s6, s6, 0xaaab
	s_lshr_b32 s7, s6, 20
	s_mul_i32 s6, s7, 24
	s_sub_i32 s0, s0, s6
	s_lshl_b32 s0, s0, 6
	s_and_b32 s6, s0, 0xffc0
	v_lshl_or_b32 v64, s7, 6, v82
	s_lshl_b32 s0, s6, 2
	v_lshl_add_u64 v[56:57], v[74:75], 0, s[0:1]
	v_or_b32_e32 v119, 4, v64
	v_or_b32_e32 v121, 8, v64
	v_or_b32_e32 v123, 12, v64
	v_or_b32_e32 v125, 16, v64
	v_or_b32_e32 v127, 20, v64
	v_or_b32_e32 v129, 24, v64
	v_or_b32_e32 v131, 28, v64
	v_or_b32_e32 v133, 32, v64
	v_or_b32_e32 v135, 36, v64
	v_or_b32_e32 v137, 40, v64
	v_or_b32_e32 v139, 44, v64
	v_or_b32_e32 v141, 48, v64
	v_or_b32_e32 v143, 52, v64
	v_or_b32_e32 v145, 56, v64
	v_or_b32_e32 v147, 60, v64
	v_mad_u64_u32 v[0:1], s[12:13], v64, s55, v[56:57]
	v_mad_u64_u32 v[4:5], s[12:13], v119, s55, v[56:57]
	v_mad_u64_u32 v[8:9], s[12:13], v121, s55, v[56:57]
	v_mad_u64_u32 v[12:13], s[12:13], v123, s55, v[56:57]
	v_mad_u64_u32 v[16:17], s[12:13], v125, s55, v[56:57]
	v_mad_u64_u32 v[20:21], s[12:13], v127, s55, v[56:57]
	v_mad_u64_u32 v[24:25], s[12:13], v129, s55, v[56:57]
	v_mad_u64_u32 v[28:29], s[12:13], v131, s55, v[56:57]
	v_mad_u64_u32 v[32:33], s[12:13], v133, s55, v[56:57]
	v_mad_u64_u32 v[36:37], s[12:13], v135, s55, v[56:57]
	v_mad_u64_u32 v[40:41], s[12:13], v137, s55, v[56:57]
	v_mad_u64_u32 v[44:45], s[12:13], v139, s55, v[56:57]
	v_mad_u64_u32 v[48:49], s[12:13], v141, s55, v[56:57]
	v_mad_u64_u32 v[52:53], s[12:13], v143, s55, v[56:57]
	v_mad_u64_u32 v[58:59], s[12:13], v145, s55, v[56:57]
	v_mad_u64_u32 v[60:61], s[12:13], v147, s55, v[56:57]
	v_lshlrev_b32_e32 v64, 2, v64
	v_lshlrev_b32_e32 v119, 2, v119
	global_load_dwordx4 v[0:3], v[0:1], off
	s_nop 0
	global_load_dwordx4 v[4:7], v[4:5], off
	s_nop 0
	global_load_dwordx4 v[8:11], v[8:9], off
	s_nop 0
	global_load_dwordx4 v[12:15], v[12:13], off
	s_nop 0
	global_load_dwordx4 v[16:19], v[16:17], off
	s_nop 0
; #define LAS __attribute__((address_space(3)))
; __host__ __device__ __forceinline__ int gate_row(int n) { if (n < 512) return n; const int base = n < 1536 ? 512 : 1536, q = n - base, h = q >> 9, t = (q & 511) >> 7, r = q & 127; return base + t * 256 + h * 128 + r; }
; template <bool GATEMAP = false>
; __device__ __forceinline__ void p0_transpose_item(const float* W, int N, bf16* WT, int ldwt, int koff, const float* gain, LAS float* scr, int item, int lane) {
;     const int nblk = N / 64, kb = item / nblk, nb = item % nblk, k0 = 64 * kb, n0 = 64 * nb; const int nd0 = GATEMAP ? gate_row(n0) : n0;
;     const int ks = lane >> 4, n4 = (lane & 15) * 4;
;     f32x4 v[16];
; #pragma unroll
;     for (int i = 0; i < 16; ++i) v[i] = *(const f32x4*)(W + (size_t)(k0 + 4 * i + ks) * N + n0 + n4);
;     if (gain) {
; #pragma unroll
;         for (int i = 0; i < 16; ++i) v[i] = v[i] * gain[k0 + 4 * i + ks];
;     }
; #pragma unroll
;     for (int i = 0; i < 16; ++i) { LAS float* d = scr + (4 * i + ks) * 65 + n4; d[0] = v[i][0]; d[1] = v[i][1]; d[2] = v[i][2]; d[3] = v[i][3]; }
	global_load_dwordx4 v[20:23], v[20:21], off
	s_nop 0
	global_load_dwordx4 v[24:27], v[24:25], off
	s_nop 0
	global_load_dwordx4 v[28:31], v[28:29], off
	s_nop 0
	global_load_dwordx4 v[32:35], v[32:33], off
	s_nop 0
	global_load_dwordx4 v[36:39], v[36:37], off
	s_nop 0
	global_load_dwordx4 v[40:43], v[40:41], off
	s_nop 0
	global_load_dwordx4 v[44:47], v[44:45], off
	s_nop 0
	global_load_dwordx4 v[48:51], v[48:49], off
	s_nop 0
	global_load_dwordx4 v[52:55], v[52:53], off
	s_nop 0
	global_load_dwordx4 v[56:59], v[58:59], off
	s_nop 0
	global_load_dwordx4 v[60:63], v[60:61], off
	s_lshl_b32 s0, s7, 7
	global_load_dword v64, v64, s[2:3]
	s_nop 0
	global_load_dword v120, v119, s[2:3]
	v_lshlrev_b32_e32 v119, 2, v121
	global_load_dword v122, v119, s[2:3]
	v_lshlrev_b32_e32 v119, 2, v123
	global_load_dword v124, v119, s[2:3]
	v_lshlrev_b32_e32 v119, 2, v125
	global_load_dword v126, v119, s[2:3]
	v_lshlrev_b32_e32 v119, 2, v127
	global_load_dword v128, v119, s[2:3]
	v_lshlrev_b32_e32 v119, 2, v129
	global_load_dword v130, v119, s[2:3]
	v_lshlrev_b32_e32 v119, 2, v131
	global_load_dword v132, v119, s[2:3]
	v_lshlrev_b32_e32 v119, 2, v133
	global_load_dword v134, v119, s[2:3]
	v_lshlrev_b32_e32 v119, 2, v135
	global_load_dword v136, v119, s[2:3]
	v_lshlrev_b32_e32 v119, 2, v137
	global_load_dword v138, v119, s[2:3]
	v_lshlrev_b32_e32 v119, 2, v139
	global_load_dword v140, v119, s[2:3]
	v_lshlrev_b32_e32 v119, 2, v141
	global_load_dword v142, v119, s[2:3]
	v_lshlrev_b32_e32 v119, 2, v143
	global_load_dword v144, v119, s[2:3]
	v_lshlrev_b32_e32 v119, 2, v145
	global_load_dword v146, v119, s[2:3]
	v_lshlrev_b32_e32 v119, 2, v147
	global_load_dword v148, v119, s[2:3]
	s_waitcnt vmcnt(15)
	v_pk_mul_f32 v[0:1], v[0:1], v[64:65] op_sel_hi:[1,0]
	v_pk_mul_f32 v[2:3], v[2:3], v[64:65] op_sel_hi:[1,0]
	s_waitcnt vmcnt(14)
	v_pk_mul_f32 v[6:7], v[6:7], v[120:121] op_sel_hi:[1,0]
	v_pk_mul_f32 v[4:5], v[4:5], v[120:121] op_sel_hi:[1,0]
	s_waitcnt vmcnt(13)
	v_pk_mul_f32 v[10:11], v[10:11], v[122:123] op_sel_hi:[1,0]
	v_pk_mul_f32 v[8:9], v[8:9], v[122:123] op_sel_hi:[1,0]
	s_waitcnt vmcnt(12)
	v_pk_mul_f32 v[14:15], v[14:15], v[124:125] op_sel_hi:[1,0]
	v_pk_mul_f32 v[12:13], v[12:13], v[124:125] op_sel_hi:[1,0]
	s_waitcnt vmcnt(11)
	v_pk_mul_f32 v[18:19], v[18:19], v[126:127] op_sel_hi:[1,0]
	v_pk_mul_f32 v[16:17], v[16:17], v[126:127] op_sel_hi:[1,0]
	s_waitcnt vmcnt(10)
	v_pk_mul_f32 v[22:23], v[22:23], v[128:129] op_sel_hi:[1,0]
	v_pk_mul_f32 v[20:21], v[20:21], v[128:129] op_sel_hi:[1,0]
	s_waitcnt vmcnt(9)
	v_pk_mul_f32 v[26:27], v[26:27], v[130:131] op_sel_hi:[1,0]
	v_pk_mul_f32 v[24:25], v[24:25], v[130:131] op_sel_hi:[1,0]
	s_waitcnt vmcnt(8)
	v_pk_mul_f32 v[30:31], v[30:31], v[132:133] op_sel_hi:[1,0]
	v_pk_mul_f32 v[28:29], v[28:29], v[132:133] op_sel_hi:[1,0]
	s_waitcnt vmcnt(7)
	v_pk_mul_f32 v[34:35], v[34:35], v[134:135] op_sel_hi:[1,0]
	v_pk_mul_f32 v[32:33], v[32:33], v[134:135] op_sel_hi:[1,0]
	s_waitcnt vmcnt(6)
	v_pk_mul_f32 v[38:39], v[38:39], v[136:137] op_sel_hi:[1,0]
	v_pk_mul_f32 v[36:37], v[36:37], v[136:137] op_sel_hi:[1,0]
	s_waitcnt vmcnt(5)
	v_pk_mul_f32 v[42:43], v[42:43], v[138:139] op_sel_hi:[1,0]
	v_pk_mul_f32 v[40:41], v[40:41], v[138:139] op_sel_hi:[1,0]
	s_waitcnt vmcnt(4)
	v_pk_mul_f32 v[46:47], v[46:47], v[140:141] op_sel_hi:[1,0]
	v_pk_mul_f32 v[44:45], v[44:45], v[140:141] op_sel_hi:[1,0]
	s_waitcnt vmcnt(3)
	v_pk_mul_f32 v[50:51], v[50:51], v[142:143] op_sel_hi:[1,0]
	v_pk_mul_f32 v[48:49], v[48:49], v[142:143] op_sel_hi:[1,0]
	s_waitcnt vmcnt(2)
	v_pk_mul_f32 v[54:55], v[54:55], v[144:145] op_sel_hi:[1,0]
	v_pk_mul_f32 v[52:53], v[52:53], v[144:145] op_sel_hi:[1,0]
	ds_write2_b32 v83, v0, v1 offset1:1
	ds_write2_b32 v83, v2, v3 offset0:2 offset1:3
	ds_write2_b32 v93, v4, v5 offset1:1
	ds_write2_b32 v94, v6, v7 offset1:1
	ds_write2_b32 v95, v8, v9 offset1:1
	ds_write2_b32 v96, v10, v11 offset1:1
	ds_write2_b32 v97, v12, v13 offset1:1
	ds_write2_b32 v98, v14, v15 offset1:1
	ds_write2_b32 v99, v16, v17 offset1:1
	ds_write2_b32 v100, v18, v19 offset1:1
	ds_write2_b32 v101, v20, v21 offset1:1
	ds_write2_b32 v102, v22, v23 offset1:1
	ds_write2_b32 v103, v24, v25 offset1:1
	ds_write2_b32 v104, v26, v27 offset1:1
	ds_write2_b32 v105, v28, v29 offset1:1
	ds_write2_b32 v106, v30, v31 offset1:1
	ds_write2_b32 v107, v32, v33 offset1:1
	ds_write2_b32 v108, v34, v35 offset1:1
	ds_write2_b32 v109, v36, v37 offset1:1
	ds_write2_b32 v110, v38, v39 offset1:1
	ds_write2_b32 v111, v40, v41 offset1:1
	ds_write2_b32 v112, v42, v43 offset1:1
	ds_write2_b32 v113, v44, v45 offset1:1
	ds_write2_b32 v114, v46, v47 offset1:1
	ds_write2_b32 v115, v48, v49 offset1:1
	ds_write2_b32 v116, v50, v51 offset1:1
	ds_write2_b32 v117, v52, v53 offset1:1
	v_add_u32_e32 v0, 0x34d8, v83
	s_waitcnt vmcnt(1)
	v_pk_mul_f32 v[56:57], v[56:57], v[146:147] op_sel_hi:[1,0]
	ds_write2_b32 v0, v54, v55 offset1:1
	v_add_u32_e32 v0, 0x38e0, v83
	v_pk_mul_f32 v[58:59], v[58:59], v[146:147] op_sel_hi:[1,0]
	ds_write2_b32 v0, v56, v57 offset1:1
	v_add_u32_e32 v0, 0x38e8, v83
	s_waitcnt vmcnt(0)
; #define LAS __attribute__((address_space(3)))
; __device__ __forceinline__ unsigned pk2(float lo, float hi) { return pg8::cvt_pk_bf16(lo, hi); }
; template <bool GATEMAP = false>
; __device__ __forceinline__ void p0_transpose_item(const float* W, int N, bf16* WT, int ldwt, int koff, const float* gain, LAS float* scr, int item, int lane) {
;     ...
;     for (int i = 0; i < 16; ++i) { LAS float* d = scr + (4 * i + ks) * 65 + n4; d[0] = v[i][0]; d[1] = v[i][1]; d[2] = v[i][2]; d[3] = v[i][3]; }
;     asm volatile("s_waitcnt lgkmcnt(0)" ::: "memory");
;     const int c = lane & 7;
; #pragma unroll
;     for (int j = 0; j < 8; ++j) { const int n = (lane >> 3) + 8 * j; const LAS float* q = scr + (8 * c) * 65 + n;
;         v4u o; o.x = pk2(q[0 * 65], q[1 * 65]); o.y = pk2(q[2 * 65], q[3 * 65]); o.z = pk2(q[4 * 65], q[5 * 65]); o.w = pk2(q[6 * 65], q[7 * 65]);
;         *(v4u*)(WT + (size_t)(nd0 + n) * ldwt + koff + k0 + 8 * c) = o; }
;     asm volatile("s_waitcnt lgkmcnt(0)" ::: "memory");
; }
	v_pk_mul_f32 v[60:61], v[60:61], v[148:149] op_sel_hi:[1,0]
	ds_write2_b32 v0, v58, v59 offset1:1
	v_add_u32_e32 v0, 0x3cf0, v83
	v_pk_mul_f32 v[62:63], v[62:63], v[148:149] op_sel_hi:[1,0]
	ds_write2_b32 v0, v60, v61 offset1:1
	v_add_u32_e32 v0, 0x3cf8, v83
	ds_write2_b32 v0, v62, v63 offset1:1
	s_waitcnt lgkmcnt(0)
	v_add_u32_e32 v10, 0x400, v85
	ds_read2_b32 v[150:151], v85 offset1:65
	ds_read2_b32 v[152:153], v85 offset0:130 offset1:195
	ds_read2_b32 v[154:155], v10 offset0:4 offset1:69
	ds_read2_b32 v[156:157], v10 offset0:134 offset1:199
	ds_read2_b32 v[158:159], v85 offset0:8 offset1:73
	ds_read2_b32 v[160:161], v85 offset0:138 offset1:203
	ds_read2_b32 v[162:163], v10 offset0:12 offset1:77
	ds_read2_b32 v[164:165], v10 offset0:142 offset1:207
	s_waitcnt lgkmcnt(7)
	v_cvt_pk_bf16_f32 v0, v150, v151
	v_or_b32_e32 v8, s6, v84
	s_waitcnt lgkmcnt(6)
	v_cvt_pk_bf16_f32 v1, v152, v153
	v_lshl_add_u64 v[6:7], v[68:69], 0, s[0:1]
	v_lshlrev_b32_e32 v64, 11, v8
	s_waitcnt lgkmcnt(5)
	v_cvt_pk_bf16_f32 v2, v154, v155
	s_waitcnt lgkmcnt(4)
	v_cvt_pk_bf16_f32 v3, v156, v157
	v_lshl_add_u64 v[8:9], v[6:7], 0, v[64:65]
	global_store_dwordx4 v[8:9], v[0:3], off
	v_or_b32_e32 v8, s6, v86
	v_lshlrev_b32_e32 v64, 11, v8
	s_waitcnt lgkmcnt(3)
	v_cvt_pk_bf16_f32 v0, v158, v159
	s_waitcnt lgkmcnt(2)
	v_cvt_pk_bf16_f32 v1, v160, v161
	s_waitcnt lgkmcnt(1)
	v_cvt_pk_bf16_f32 v2, v162, v163
	s_waitcnt lgkmcnt(0)
	v_cvt_pk_bf16_f32 v3, v164, v165
	v_lshl_add_u64 v[8:9], v[6:7], 0, v[64:65]
	global_store_dwordx4 v[8:9], v[0:3], off
	v_or_b32_e32 v8, s6, v87
	v_lshlrev_b32_e32 v64, 11, v8
	ds_read2_b32 v[150:151], v85 offset0:16 offset1:81
	ds_read2_b32 v[152:153], v85 offset0:146 offset1:211
	ds_read2_b32 v[154:155], v10 offset0:20 offset1:85
	ds_read2_b32 v[156:157], v10 offset0:150 offset1:215
	ds_read2_b32 v[158:159], v85 offset0:24 offset1:89
	ds_read2_b32 v[160:161], v85 offset0:154 offset1:219
	ds_read2_b32 v[162:163], v10 offset0:28 offset1:93
	ds_read2_b32 v[164:165], v10 offset0:158 offset1:223
	s_waitcnt lgkmcnt(7)
	v_cvt_pk_bf16_f32 v0, v150, v151
	s_waitcnt lgkmcnt(6)
	v_cvt_pk_bf16_f32 v1, v152, v153
	s_waitcnt lgkmcnt(5)
	v_cvt_pk_bf16_f32 v2, v154, v155
	s_waitcnt lgkmcnt(4)
	v_cvt_pk_bf16_f32 v3, v156, v157
	v_lshl_add_u64 v[8:9], v[6:7], 0, v[64:65]
	global_store_dwordx4 v[8:9], v[0:3], off
	v_or_b32_e32 v8, s6, v88
	v_lshlrev_b32_e32 v64, 11, v8
	s_waitcnt lgkmcnt(3)
	v_cvt_pk_bf16_f32 v0, v158, v159
	s_waitcnt lgkmcnt(2)
	v_cvt_pk_bf16_f32 v1, v160, v161
	s_waitcnt lgkmcnt(1)
	v_cvt_pk_bf16_f32 v2, v162, v163
	s_waitcnt lgkmcnt(0)
	v_cvt_pk_bf16_f32 v3, v164, v165
	v_lshl_add_u64 v[8:9], v[6:7], 0, v[64:65]
	global_store_dwordx4 v[8:9], v[0:3], off
	v_or_b32_e32 v8, s6, v89
	v_lshlrev_b32_e32 v64, 11, v8
	ds_read2_b32 v[150:151], v85 offset0:32 offset1:97
	ds_read2_b32 v[152:153], v85 offset0:162 offset1:227
	ds_read2_b32 v[154:155], v10 offset0:36 offset1:101
	ds_read2_b32 v[156:157], v10 offset0:166 offset1:231
	ds_read2_b32 v[158:159], v85 offset0:40 offset1:105
	ds_read2_b32 v[160:161], v85 offset0:170 offset1:235
	ds_read2_b32 v[162:163], v10 offset0:44 offset1:109
	ds_read2_b32 v[164:165], v10 offset0:174 offset1:239
	s_waitcnt lgkmcnt(7)
	v_cvt_pk_bf16_f32 v0, v150, v151
	s_waitcnt lgkmcnt(6)
	v_cvt_pk_bf16_f32 v1, v152, v153
	s_waitcnt lgkmcnt(5)
	v_cvt_pk_bf16_f32 v2, v154, v155
	s_waitcnt lgkmcnt(4)
	v_cvt_pk_bf16_f32 v3, v156, v157
	v_lshl_add_u64 v[8:9], v[6:7], 0, v[64:65]
	global_store_dwordx4 v[8:9], v[0:3], off
	v_or_b32_e32 v8, s6, v90
	v_lshlrev_b32_e32 v64, 11, v8
	s_waitcnt lgkmcnt(3)
	v_cvt_pk_bf16_f32 v0, v158, v159
	s_waitcnt lgkmcnt(2)
	v_cvt_pk_bf16_f32 v1, v160, v161
	s_waitcnt lgkmcnt(1)
	v_cvt_pk_bf16_f32 v2, v162, v163
	s_waitcnt lgkmcnt(0)
	v_cvt_pk_bf16_f32 v3, v164, v165
	v_lshl_add_u64 v[8:9], v[6:7], 0, v[64:65]
	global_store_dwordx4 v[8:9], v[0:3], off
	v_or_b32_e32 v8, s6, v91
	v_lshlrev_b32_e32 v64, 11, v8
	ds_read2_b32 v[150:151], v85 offset0:48 offset1:113
	ds_read2_b32 v[152:153], v85 offset0:178 offset1:243
	ds_read2_b32 v[154:155], v10 offset0:52 offset1:117
	ds_read2_b32 v[156:157], v10 offset0:182 offset1:247
	ds_read2_b32 v[158:159], v85 offset0:56 offset1:121
	ds_read2_b32 v[160:161], v85 offset0:186 offset1:251
	ds_read2_b32 v[162:163], v10 offset0:60 offset1:125
	ds_read2_b32 v[164:165], v10 offset0:190 offset1:255
	s_waitcnt lgkmcnt(7)
	v_cvt_pk_bf16_f32 v0, v150, v151
	s_waitcnt lgkmcnt(6)
	v_cvt_pk_bf16_f32 v1, v152, v153
	s_waitcnt lgkmcnt(5)
	v_cvt_pk_bf16_f32 v2, v154, v155
	s_waitcnt lgkmcnt(4)
	v_cvt_pk_bf16_f32 v3, v156, v157
	v_lshl_add_u64 v[8:9], v[6:7], 0, v[64:65]
	global_store_dwordx4 v[8:9], v[0:3], off
	s_waitcnt lgkmcnt(3)
	s_nop 0
	v_cvt_pk_bf16_f32 v0, v158, v159
	s_waitcnt lgkmcnt(2)
	v_cvt_pk_bf16_f32 v1, v160, v161
	s_waitcnt lgkmcnt(1)
	v_cvt_pk_bf16_f32 v2, v162, v163
	s_waitcnt lgkmcnt(0)
	v_cvt_pk_bf16_f32 v3, v164, v165
	v_or_b32_e32 v4, s6, v92
	v_lshlrev_b32_e32 v64, 11, v4
	v_lshl_add_u64 v[4:5], v[6:7], 0, v[64:65]
	global_store_dwordx4 v[4:5], v[0:3], off
	s_waitcnt lgkmcnt(0)

; #define LAS __attribute__((address_space(3)))
; __device__ __forceinline__ unsigned pk2(float lo, float hi) { return pg8::cvt_pk_bf16(lo, hi); }
; __host__ __device__ __forceinline__ int gate_row(int n) { if (n < 512) return n; const int base = n < 1536 ? 512 : 1536, q = n - base, h = q >> 9, t = (q & 511) >> 7, r = q & 127; return base + t * 256 + h * 128 + r; }
; template <bool GATEMAP = false>
; __device__ __forceinline__ void p0_transpose_item(const float* W, int N, bf16* WT, int ldwt, int koff, const float* gain, LAS float* scr, int item, int lane) {
;     const int nblk = N / 64, kb = item / nblk, nb = item % nblk, k0 = 64 * kb, n0 = 64 * nb; const int nd0 = GATEMAP ? gate_row(n0) : n0;
;     const int ks = lane >> 4, n4 = (lane & 15) * 4;
;     f32x4 v[16];
; #pragma unroll
;     for (int i = 0; i < 16; ++i) v[i] = *(const f32x4*)(W + (size_t)(k0 + 4 * i + ks) * N + n0 + n4);
;     if (gain) {
; #pragma unroll
;         for (int i = 0; i < 16; ++i) v[i] = v[i] * gain[k0 + 4 * i + ks];
;     }
; #pragma unroll
;     for (int i = 0; i < 16; ++i) { LAS float* d = scr + (4 * i + ks) * 65 + n4; d[0] = v[i][0]; d[1] = v[i][1]; d[2] = v[i][2]; d[3] = v[i][3]; }
;     asm volatile("s_waitcnt lgkmcnt(0)" ::: "memory");
;     const int c = lane & 7;
; #pragma unroll
;     for (int j = 0; j < 8; ++j) { const int n = (lane >> 3) + 8 * j; const LAS float* q = scr + (8 * c) * 65 + n;
;         v4u o; o.x = pk2(q[0 * 65], q[1 * 65]); o.y = pk2(q[2 * 65], q[3 * 65]); o.z = pk2(q[4 * 65], q[5 * 65]); o.w = pk2(q[6 * 65], q[7 * 65]);
;         *(v4u*)(WT + (size_t)(nd0 + n) * ldwt + koff + k0 + 8 * c) = o; }
;     asm volatile("s_waitcnt lgkmcnt(0)" ::: "memory");
; }
; template <int PART>
; __device__ __forceinline__ void phase_prologue_late(const Params& p, LAS unsigned char* lds, int cu0) {
;     ...
;             if (r < I_W1) { p0_transpose_item(p.in[22], FF, (bf16*)(ws + WS_W1_0), D, 0, p.in[6], scr, r, lane); continue; } r -= I_W1;
.LBB0_174:
	s_waitcnt vmcnt(15)
	ds_write2_b32 v83, v4, v5 offset1:1
	ds_write2_b32 v83, v6, v7 offset0:2 offset1:3
	s_waitcnt vmcnt(14)
	ds_write2_b32 v93, v0, v1 offset1:1
	ds_write2_b32 v94, v2, v3 offset1:1
	s_waitcnt vmcnt(13)
	ds_write2_b32 v95, v12, v13 offset1:1
	ds_write2_b32 v96, v14, v15 offset1:1
	s_waitcnt vmcnt(12)
	ds_write2_b32 v97, v8, v9 offset1:1
	ds_write2_b32 v98, v10, v11 offset1:1
	s_waitcnt vmcnt(11)
	ds_write2_b32 v99, v20, v21 offset1:1
	ds_write2_b32 v100, v22, v23 offset1:1
	s_waitcnt vmcnt(10)
	ds_write2_b32 v101, v16, v17 offset1:1
	ds_write2_b32 v102, v18, v19 offset1:1
	s_waitcnt vmcnt(9)
	ds_write2_b32 v103, v28, v29 offset1:1
	ds_write2_b32 v104, v30, v31 offset1:1
	s_waitcnt vmcnt(8)
	ds_write2_b32 v105, v24, v25 offset1:1
	ds_write2_b32 v106, v26, v27 offset1:1
	s_waitcnt vmcnt(7)
	ds_write2_b32 v107, v36, v37 offset1:1
	ds_write2_b32 v108, v38, v39 offset1:1
	s_waitcnt vmcnt(6)
	ds_write2_b32 v109, v32, v33 offset1:1
	ds_write2_b32 v110, v34, v35 offset1:1
	s_waitcnt vmcnt(5)
	ds_write2_b32 v111, v44, v45 offset1:1
	ds_write2_b32 v112, v46, v47 offset1:1
	s_waitcnt vmcnt(4)
	ds_write2_b32 v113, v40, v41 offset1:1
	ds_write2_b32 v114, v42, v43 offset1:1
	s_waitcnt vmcnt(3)
	ds_write2_b32 v115, v52, v53 offset1:1
	ds_write2_b32 v116, v54, v55 offset1:1
	s_waitcnt vmcnt(2)
	ds_write2_b32 v117, v48, v49 offset1:1
	v_add_u32_e32 v0, 0x34d8, v83
	ds_write2_b32 v0, v50, v51 offset1:1
	v_add_u32_e32 v0, 0x38e0, v83
	s_waitcnt vmcnt(1)
	ds_write2_b32 v0, v60, v61 offset1:1
	v_add_u32_e32 v0, 0x38e8, v83
	ds_write2_b32 v0, v62, v63 offset1:1
	v_add_u32_e32 v0, 0x3cf0, v83
	s_waitcnt vmcnt(0)
	ds_write2_b32 v0, v56, v57 offset1:1
	v_add_u32_e32 v0, 0x3cf8, v83
	ds_write2_b32 v0, v58, v59 offset1:1
	s_waitcnt lgkmcnt(0)
	v_add_u32_e32 v10, 0x400, v85
	ds_read2_b32 v[150:151], v85 offset1:65
	ds_read2_b32 v[152:153], v85 offset0:130 offset1:195
	ds_read2_b32 v[154:155], v10 offset0:4 offset1:69
	ds_read2_b32 v[156:157], v10 offset0:134 offset1:199
	ds_read2_b32 v[158:159], v85 offset0:8 offset1:73
	ds_read2_b32 v[160:161], v85 offset0:138 offset1:203
	ds_read2_b32 v[162:163], v10 offset0:12 offset1:77
	ds_read2_b32 v[164:165], v10 offset0:142 offset1:207
	s_waitcnt lgkmcnt(7)
	v_cvt_pk_bf16_f32 v0, v150, v151
	s_lshl_b32 s0, s7, 1
	v_or_b32_e32 v8, s6, v84
	s_waitcnt lgkmcnt(6)
	v_cvt_pk_bf16_f32 v1, v152, v153
	v_lshl_add_u64 v[6:7], v[70:71], 0, s[0:1]
	v_lshlrev_b32_e32 v64, 11, v8
	s_waitcnt lgkmcnt(5)
	v_cvt_pk_bf16_f32 v2, v154, v155
	s_waitcnt lgkmcnt(4)
	v_cvt_pk_bf16_f32 v3, v156, v157
	v_lshl_add_u64 v[8:9], v[6:7], 0, v[64:65]
	global_store_dwordx4 v[8:9], v[0:3], off
	v_or_b32_e32 v8, s6, v86
	v_lshlrev_b32_e32 v64, 11, v8
	s_waitcnt lgkmcnt(3)
	v_cvt_pk_bf16_f32 v0, v158, v159
	s_waitcnt lgkmcnt(2)
	v_cvt_pk_bf16_f32 v1, v160, v161
	s_waitcnt lgkmcnt(1)
	v_cvt_pk_bf16_f32 v2, v162, v163
	s_waitcnt lgkmcnt(0)
	v_cvt_pk_bf16_f32 v3, v164, v165
	v_lshl_add_u64 v[8:9], v[6:7], 0, v[64:65]
	global_store_dwordx4 v[8:9], v[0:3], off
	v_or_b32_e32 v8, s6, v87
	v_lshlrev_b32_e32 v64, 11, v8
	ds_read2_b32 v[150:151], v85 offset0:16 offset1:81
	ds_read2_b32 v[152:153], v85 offset0:146 offset1:211
	ds_read2_b32 v[154:155], v10 offset0:20 offset1:85
	ds_read2_b32 v[156:157], v10 offset0:150 offset1:215
	ds_read2_b32 v[158:159], v85 offset0:24 offset1:89
	ds_read2_b32 v[160:161], v85 offset0:154 offset1:219
	ds_read2_b32 v[162:163], v10 offset0:28 offset1:93
	ds_read2_b32 v[164:165], v10 offset0:158 offset1:223
	s_waitcnt lgkmcnt(7)
	v_cvt_pk_bf16_f32 v0, v150, v151
	s_waitcnt lgkmcnt(6)
	v_cvt_pk_bf16_f32 v1, v152, v153
	s_waitcnt lgkmcnt(5)
	v_cvt_pk_bf16_f32 v2, v154, v155
	s_waitcnt lgkmcnt(4)
	v_cvt_pk_bf16_f32 v3, v156, v157
	v_lshl_add_u64 v[8:9], v[6:7], 0, v[64:65]
	global_store_dwordx4 v[8:9], v[0:3], off
	v_or_b32_e32 v8, s6, v88
	v_lshlrev_b32_e32 v64, 11, v8
	s_waitcnt lgkmcnt(3)
	v_cvt_pk_bf16_f32 v0, v158, v159
	s_waitcnt lgkmcnt(2)
	v_cvt_pk_bf16_f32 v1, v160, v161
	s_waitcnt lgkmcnt(1)
	v_cvt_pk_bf16_f32 v2, v162, v163
	s_waitcnt lgkmcnt(0)
	v_cvt_pk_bf16_f32 v3, v164, v165
	v_lshl_add_u64 v[8:9], v[6:7], 0, v[64:65]
	global_store_dwordx4 v[8:9], v[0:3], off
	v_or_b32_e32 v8, s6, v89
	v_lshlrev_b32_e32 v64, 11, v8
	ds_read2_b32 v[150:151], v85 offset0:32 offset1:97
	ds_read2_b32 v[152:153], v85 offset0:162 offset1:227
	ds_read2_b32 v[154:155], v10 offset0:36 offset1:101
	ds_read2_b32 v[156:157], v10 offset0:166 offset1:231
	ds_read2_b32 v[158:159], v85 offset0:40 offset1:105
	ds_read2_b32 v[160:161], v85 offset0:170 offset1:235
	ds_read2_b32 v[162:163], v10 offset0:44 offset1:109
	ds_read2_b32 v[164:165], v10 offset0:174 offset1:239
	s_waitcnt lgkmcnt(7)
	v_cvt_pk_bf16_f32 v0, v150, v151
	s_waitcnt lgkmcnt(6)
	v_cvt_pk_bf16_f32 v1, v152, v153
	s_waitcnt lgkmcnt(5)
	v_cvt_pk_bf16_f32 v2, v154, v155
	s_waitcnt lgkmcnt(4)
	v_cvt_pk_bf16_f32 v3, v156, v157
	v_lshl_add_u64 v[8:9], v[6:7], 0, v[64:65]
	global_store_dwordx4 v[8:9], v[0:3], off
	v_or_b32_e32 v8, s6, v90
	v_lshlrev_b32_e32 v64, 11, v8
	s_waitcnt lgkmcnt(3)
	v_cvt_pk_bf16_f32 v0, v158, v159
	s_waitcnt lgkmcnt(2)
	v_cvt_pk_bf16_f32 v1, v160, v161
	s_waitcnt lgkmcnt(1)
	v_cvt_pk_bf16_f32 v2, v162, v163
	s_waitcnt lgkmcnt(0)
	v_cvt_pk_bf16_f32 v3, v164, v165
	v_lshl_add_u64 v[8:9], v[6:7], 0, v[64:65]
	global_store_dwordx4 v[8:9], v[0:3], off
	v_or_b32_e32 v8, s6, v91
	v_lshlrev_b32_e32 v64, 11, v8
	ds_read2_b32 v[150:151], v85 offset0:48 offset1:113
	ds_read2_b32 v[152:153], v85 offset0:178 offset1:243
	ds_read2_b32 v[154:155], v10 offset0:52 offset1:117
	ds_read2_b32 v[156:157], v10 offset0:182 offset1:247
	ds_read2_b32 v[158:159], v85 offset0:56 offset1:121
	ds_read2_b32 v[160:161], v85 offset0:186 offset1:251
	ds_read2_b32 v[162:163], v10 offset0:60 offset1:125
	ds_read2_b32 v[164:165], v10 offset0:190 offset1:255
	s_waitcnt lgkmcnt(7)
	v_cvt_pk_bf16_f32 v0, v150, v151
	s_waitcnt lgkmcnt(6)
	v_cvt_pk_bf16_f32 v1, v152, v153
	s_waitcnt lgkmcnt(5)
	v_cvt_pk_bf16_f32 v2, v154, v155
	s_waitcnt lgkmcnt(4)
	v_cvt_pk_bf16_f32 v3, v156, v157
	v_lshl_add_u64 v[8:9], v[6:7], 0, v[64:65]
	global_store_dwordx4 v[8:9], v[0:3], off
	s_waitcnt lgkmcnt(3)
	s_nop 0
	v_cvt_pk_bf16_f32 v0, v158, v159
	s_waitcnt lgkmcnt(2)
	v_cvt_pk_bf16_f32 v1, v160, v161
	s_waitcnt lgkmcnt(1)
	v_cvt_pk_bf16_f32 v2, v162, v163
	v_or_b32_e32 v3, s6, v92
	v_lshlrev_b32_e32 v64, 11, v3
	s_waitcnt lgkmcnt(0)
	v_cvt_pk_bf16_f32 v3, v164, v165
	v_lshl_add_u64 v[4:5], v[6:7], 0, v[64:65]
	global_store_dwordx4 v[4:5], v[0:3], off
	s_waitcnt lgkmcnt(0)

; #define LAS __attribute__((address_space(3)))
; __host__ __device__ __forceinline__ int gate_row(int n) { if (n < 512) return n; const int base = n < 1536 ? 512 : 1536, q = n - base, h = q >> 9, t = (q & 511) >> 7, r = q & 127; return base + t * 256 + h * 128 + r; }
; template <bool GATEMAP = false>
; __device__ __forceinline__ void p0_transpose_item(const float* W, int N, bf16* WT, int ldwt, int koff, const float* gain, LAS float* scr, int item, int lane) {
;     const int nblk = N / 64, kb = item / nblk, nb = item % nblk, k0 = 64 * kb, n0 = 64 * nb; const int nd0 = GATEMAP ? gate_row(n0) : n0;
;     const int ks = lane >> 4, n4 = (lane & 15) * 4;
;     f32x4 v[16];
; #pragma unroll
;     for (int i = 0; i < 16; ++i) v[i] = *(const f32x4*)(W + (size_t)(k0 + 4 * i + ks) * N + n0 + n4);
;     if (gain) {
; #pragma unroll
;         for (int i = 0; i < 16; ++i) v[i] = v[i] * gain[k0 + 4 * i + ks];
;     }
; #pragma unroll
;     for (int i = 0; i < 16; ++i) { LAS float* d = scr + (4 * i + ks) * 65 + n4; d[0] = v[i][0]; d[1] = v[i][1]; d[2] = v[i][2]; d[3] = v[i][3]; }
;     asm volatile("s_waitcnt lgkmcnt(0)" ::: "memory");
; template <int PART>
; __device__ __forceinline__ void phase_prologue_late(const Params& p, LAS unsigned char* lds, int cu0) {
;     ...
;             if (r < 16 * 16) { p0_transpose_item(p.in[13], D, (bf16*)(ws + WS_WOUT0), D, 0, nullptr, scr, r, lane); continue; } r -= 16 * 16;
.LBB0_176:
	s_andn2_b64 vcc, exec, s[6:7]
	s_cbranch_vccnz .LBB0_163
	s_ashr_i32 s0, s8, 31
	s_lshr_b32 s0, s0, 28
	s_add_i32 s0, s8, s0
	s_ashr_i32 s0, s0, 4
	s_lshl_b32 s50, s0, 6
	s_lshl_b32 s0, s0, 10
	v_or_b32_e32 v60, s50, v82
	s_sub_i32 s6, s29, s0
	v_or_b32_e32 v2, 4, v60
	v_or_b32_e32 v8, 8, v60
	v_or_b32_e32 v10, 12, v60
	v_or_b32_e32 v16, 16, v60
	v_or_b32_e32 v18, 20, v60
	v_or_b32_e32 v24, 24, v60
	v_or_b32_e32 v26, 28, v60
	v_or_b32_e32 v32, 32, v60
	v_or_b32_e32 v34, 36, v60
	v_or_b32_e32 v40, 40, v60
	v_or_b32_e32 v42, 44, v60
	v_or_b32_e32 v48, 48, v60
	v_or_b32_e32 v50, 52, v60
	s_ashr_i32 s7, s6, 31
	v_ashrrev_i32_e32 v61, 31, v60
	v_ashrrev_i32_e32 v3, 31, v2
	v_ashrrev_i32_e32 v9, 31, v8
	v_ashrrev_i32_e32 v11, 31, v10
	v_ashrrev_i32_e32 v17, 31, v16
	v_ashrrev_i32_e32 v19, 31, v18
	v_ashrrev_i32_e32 v25, 31, v24
	v_ashrrev_i32_e32 v27, 31, v26
	v_ashrrev_i32_e32 v33, 31, v32
	v_ashrrev_i32_e32 v35, 31, v34
	v_ashrrev_i32_e32 v41, 31, v40
	v_ashrrev_i32_e32 v43, 31, v42
	v_ashrrev_i32_e32 v49, 31, v48
	v_ashrrev_i32_e32 v51, 31, v50
	v_lshl_add_u64 v[62:63], s[6:7], 2, v[78:79]
	v_lshlrev_b64 v[0:1], 12, v[60:61]
	v_lshlrev_b64 v[2:3], 12, v[2:3]
	v_lshlrev_b64 v[8:9], 12, v[8:9]
	v_lshlrev_b64 v[10:11], 12, v[10:11]
	v_lshlrev_b64 v[16:17], 12, v[16:17]
	v_lshlrev_b64 v[18:19], 12, v[18:19]
	v_lshlrev_b64 v[24:25], 12, v[24:25]
	v_lshlrev_b64 v[26:27], 12, v[26:27]
	v_lshlrev_b64 v[32:33], 12, v[32:33]
	v_lshlrev_b64 v[34:35], 12, v[34:35]
	v_lshlrev_b64 v[40:41], 12, v[40:41]
	v_lshlrev_b64 v[42:43], 12, v[42:43]
	v_lshlrev_b64 v[48:49], 12, v[48:49]
	v_lshlrev_b64 v[50:51], 12, v[50:51]
	v_or_b32_e32 v56, 56, v60
	v_lshl_add_u64 v[0:1], v[62:63], 0, v[0:1]
	v_lshl_add_u64 v[4:5], v[62:63], 0, v[2:3]
	v_lshl_add_u64 v[8:9], v[62:63], 0, v[8:9]
	v_lshl_add_u64 v[12:13], v[62:63], 0, v[10:11]
	v_lshl_add_u64 v[16:17], v[62:63], 0, v[16:17]
	v_lshl_add_u64 v[20:21], v[62:63], 0, v[18:19]
	v_lshl_add_u64 v[24:25], v[62:63], 0, v[24:25]
	v_lshl_add_u64 v[28:29], v[62:63], 0, v[26:27]
	v_lshl_add_u64 v[32:33], v[62:63], 0, v[32:33]
	v_lshl_add_u64 v[36:37], v[62:63], 0, v[34:35]
	v_lshl_add_u64 v[40:41], v[62:63], 0, v[40:41]
	v_lshl_add_u64 v[44:45], v[62:63], 0, v[42:43]
	v_lshl_add_u64 v[48:49], v[62:63], 0, v[48:49]
	v_lshl_add_u64 v[52:53], v[62:63], 0, v[50:51]
	v_ashrrev_i32_e32 v57, 31, v56
	global_load_dwordx4 v[0:3], v[0:1], off
	s_nop 0
	global_load_dwordx4 v[4:7], v[4:5], off
	s_nop 0
	global_load_dwordx4 v[8:11], v[8:9], off
	s_nop 0
	global_load_dwordx4 v[12:15], v[12:13], off
	s_nop 0
	global_load_dwordx4 v[16:19], v[16:17], off
	s_nop 0
	global_load_dwordx4 v[20:23], v[20:21], off
	s_nop 0
	global_load_dwordx4 v[24:27], v[24:25], off
	s_nop 0
	global_load_dwordx4 v[28:31], v[28:29], off
	s_nop 0
	global_load_dwordx4 v[32:35], v[32:33], off
	s_nop 0
	global_load_dwordx4 v[36:39], v[36:37], off
	s_nop 0
	global_load_dwordx4 v[40:43], v[40:41], off
	s_nop 0
	global_load_dwordx4 v[44:47], v[44:45], off
	s_nop 0
	global_load_dwordx4 v[48:51], v[48:49], off
	s_nop 0
	global_load_dwordx4 v[52:55], v[52:53], off
	v_lshlrev_b64 v[56:57], 12, v[56:57]
	v_or_b32_e32 v60, 60, v60
	v_lshl_add_u64 v[56:57], v[62:63], 0, v[56:57]
	v_ashrrev_i32_e32 v61, 31, v60
	global_load_dwordx4 v[56:59], v[56:57], off
	v_lshlrev_b64 v[60:61], 12, v[60:61]
	v_lshl_add_u64 v[60:61], v[62:63], 0, v[60:61]
	global_load_dwordx4 v[60:63], v[60:61], off
	s_ashr_i32 s51, s50, 31
	s_waitcnt vmcnt(15)
	ds_write2_b32 v83, v0, v1 offset1:1
	ds_write2_b32 v83, v2, v3 offset0:2 offset1:3
	s_waitcnt vmcnt(14)
	ds_write2_b32 v93, v4, v5 offset1:1
	ds_write2_b32 v94, v6, v7 offset1:1
	s_waitcnt vmcnt(13)
	ds_write2_b32 v95, v8, v9 offset1:1
	ds_write2_b32 v96, v10, v11 offset1:1
	s_waitcnt vmcnt(12)
	ds_write2_b32 v97, v12, v13 offset1:1
	ds_write2_b32 v98, v14, v15 offset1:1
	s_waitcnt vmcnt(11)
	ds_write2_b32 v99, v16, v17 offset1:1
	ds_write2_b32 v100, v18, v19 offset1:1
	s_waitcnt vmcnt(10)
	ds_write2_b32 v101, v20, v21 offset1:1
	ds_write2_b32 v102, v22, v23 offset1:1
	s_waitcnt vmcnt(9)
	ds_write2_b32 v103, v24, v25 offset1:1
	ds_write2_b32 v104, v26, v27 offset1:1
	s_waitcnt vmcnt(8)
	ds_write2_b32 v105, v28, v29 offset1:1
	ds_write2_b32 v106, v30, v31 offset1:1
	s_waitcnt vmcnt(7)
	ds_write2_b32 v107, v32, v33 offset1:1
	ds_write2_b32 v108, v34, v35 offset1:1
	s_waitcnt vmcnt(6)
	ds_write2_b32 v109, v36, v37 offset1:1
	ds_write2_b32 v110, v38, v39 offset1:1
	s_waitcnt vmcnt(5)
	ds_write2_b32 v111, v40, v41 offset1:1
	ds_write2_b32 v112, v42, v43 offset1:1
	s_waitcnt vmcnt(4)
	ds_write2_b32 v113, v44, v45 offset1:1
	ds_write2_b32 v114, v46, v47 offset1:1
	s_waitcnt vmcnt(3)
	ds_write2_b32 v115, v48, v49 offset1:1
	ds_write2_b32 v116, v50, v51 offset1:1
	s_waitcnt vmcnt(2)
	ds_write2_b32 v117, v52, v53 offset1:1
	v_add_u32_e32 v0, 0x34d8, v83
	ds_write2_b32 v0, v54, v55 offset1:1
	v_add_u32_e32 v0, 0x38e0, v83
	v_add_u32_e32 v12, 0x400, v85
	s_waitcnt vmcnt(1)
	ds_write2_b32 v0, v56, v57 offset1:1
	v_add_u32_e32 v0, 0x38e8, v83
	ds_write2_b32 v0, v58, v59 offset1:1
	v_add_u32_e32 v0, 0x3cf0, v83
	s_waitcnt vmcnt(0)
; #define LAS __attribute__((address_space(3)))
; __device__ __forceinline__ unsigned pk2(float lo, float hi) { return pg8::cvt_pk_bf16(lo, hi); }
; template <bool GATEMAP = false>
; __device__ __forceinline__ void p0_transpose_item(const float* W, int N, bf16* WT, int ldwt, int koff, const float* gain, LAS float* scr, int item, int lane) {
;     ...
;     for (int i = 0; i < 16; ++i) { LAS float* d = scr + (4 * i + ks) * 65 + n4; d[0] = v[i][0]; d[1] = v[i][1]; d[2] = v[i][2]; d[3] = v[i][3]; }
;     asm volatile("s_waitcnt lgkmcnt(0)" ::: "memory");
;     const int c = lane & 7;
; #pragma unroll
;     for (int j = 0; j < 8; ++j) { const int n = (lane >> 3) + 8 * j; const LAS float* q = scr + (8 * c) * 65 + n;
;         v4u o; o.x = pk2(q[0 * 65], q[1 * 65]); o.y = pk2(q[2 * 65], q[3 * 65]); o.z = pk2(q[4 * 65], q[5 * 65]); o.w = pk2(q[6 * 65], q[7 * 65]);
;         *(v4u*)(WT + (size_t)(nd0 + n) * ldwt + koff + k0 + 8 * c) = o; }
;     asm volatile("s_waitcnt lgkmcnt(0)" ::: "memory");
	ds_write2_b32 v0, v60, v61 offset1:1
	v_add_u32_e32 v0, 0x3cf8, v83
	ds_write2_b32 v0, v62, v63 offset1:1
	s_waitcnt lgkmcnt(0)
	ds_read2_b32 v[150:151], v85 offset1:65
	ds_read2_b32 v[152:153], v85 offset0:130 offset1:195
	ds_read2_b32 v[154:155], v12 offset0:4 offset1:69
	ds_read2_b32 v[156:157], v12 offset0:134 offset1:199
	ds_read2_b32 v[158:159], v85 offset0:8 offset1:73
	ds_read2_b32 v[160:161], v85 offset0:138 offset1:203
	ds_read2_b32 v[162:163], v12 offset0:12 offset1:77
	ds_read2_b32 v[164:165], v12 offset0:142 offset1:207
	s_waitcnt lgkmcnt(7)
	v_cvt_pk_bf16_f32 v0, v150, v151
	s_waitcnt lgkmcnt(6)
	v_cvt_pk_bf16_f32 v1, v152, v153
	s_waitcnt lgkmcnt(5)
	v_cvt_pk_bf16_f32 v2, v154, v155
	s_waitcnt lgkmcnt(4)
	v_cvt_pk_bf16_f32 v3, v156, v157
	v_add_u32_e32 v4, s6, v84
	v_ashrrev_i32_e32 v5, 31, v4
	v_lshl_add_u64 v[6:7], s[50:51], 1, v[72:73]
	v_lshlrev_b64 v[10:11], 11, v[4:5]
	v_lshl_add_u64 v[10:11], v[6:7], 0, v[10:11]
	global_store_dwordx4 v[10:11], v[0:3], off
	s_waitcnt lgkmcnt(3)
	s_nop 0
	v_cvt_pk_bf16_f32 v0, v158, v159
	s_waitcnt lgkmcnt(2)
	v_cvt_pk_bf16_f32 v1, v160, v161
	s_waitcnt lgkmcnt(1)
	v_cvt_pk_bf16_f32 v2, v162, v163
	s_waitcnt lgkmcnt(0)
	v_cvt_pk_bf16_f32 v3, v164, v165
	v_add_u32_e32 v8, 8, v4
	v_ashrrev_i32_e32 v9, 31, v8
	v_lshlrev_b64 v[8:9], 11, v[8:9]
	v_lshl_add_u64 v[8:9], v[6:7], 0, v[8:9]
	global_store_dwordx4 v[8:9], v[0:3], off
	ds_read2_b32 v[150:151], v85 offset0:16 offset1:81
	ds_read2_b32 v[152:153], v85 offset0:146 offset1:211
	ds_read2_b32 v[154:155], v12 offset0:20 offset1:85
	ds_read2_b32 v[156:157], v12 offset0:150 offset1:215
	ds_read2_b32 v[158:159], v85 offset0:24 offset1:89
	ds_read2_b32 v[160:161], v85 offset0:154 offset1:219
	ds_read2_b32 v[162:163], v12 offset0:28 offset1:93
	ds_read2_b32 v[164:165], v12 offset0:158 offset1:223
	s_waitcnt lgkmcnt(7)
	s_nop 0
	v_cvt_pk_bf16_f32 v0, v150, v151
	s_waitcnt lgkmcnt(6)
	v_cvt_pk_bf16_f32 v1, v152, v153
	s_waitcnt lgkmcnt(5)
	v_cvt_pk_bf16_f32 v2, v154, v155
	s_waitcnt lgkmcnt(4)
	v_cvt_pk_bf16_f32 v3, v156, v157
	v_add_u32_e32 v8, 16, v4
	v_ashrrev_i32_e32 v9, 31, v8
	v_lshlrev_b64 v[8:9], 11, v[8:9]
	v_lshl_add_u64 v[8:9], v[6:7], 0, v[8:9]
	global_store_dwordx4 v[8:9], v[0:3], off
	s_waitcnt lgkmcnt(3)
	s_nop 0
	v_cvt_pk_bf16_f32 v0, v158, v159
	s_waitcnt lgkmcnt(2)
	v_cvt_pk_bf16_f32 v1, v160, v161
	s_waitcnt lgkmcnt(1)
	v_cvt_pk_bf16_f32 v2, v162, v163
	s_waitcnt lgkmcnt(0)
	v_cvt_pk_bf16_f32 v3, v164, v165
	v_add_u32_e32 v8, 24, v4
	v_ashrrev_i32_e32 v9, 31, v8
	v_lshlrev_b64 v[8:9], 11, v[8:9]
	v_lshl_add_u64 v[8:9], v[6:7], 0, v[8:9]
	global_store_dwordx4 v[8:9], v[0:3], off
	ds_read2_b32 v[150:151], v85 offset0:32 offset1:97
	ds_read2_b32 v[152:153], v85 offset0:162 offset1:227
	ds_read2_b32 v[154:155], v12 offset0:36 offset1:101
	ds_read2_b32 v[156:157], v12 offset0:166 offset1:231
	ds_read2_b32 v[158:159], v85 offset0:40 offset1:105
	ds_read2_b32 v[160:161], v85 offset0:170 offset1:235
	ds_read2_b32 v[162:163], v12 offset0:44 offset1:109
	ds_read2_b32 v[164:165], v12 offset0:174 offset1:239
	s_waitcnt lgkmcnt(7)
	s_nop 0
	v_cvt_pk_bf16_f32 v0, v150, v151
	v_add_u32_e32 v10, 32, v4
	v_ashrrev_i32_e32 v11, 31, v10
	v_lshlrev_b64 v[10:11], 11, v[10:11]
	s_waitcnt lgkmcnt(6)
	v_cvt_pk_bf16_f32 v1, v152, v153
	v_lshl_add_u64 v[10:11], v[6:7], 0, v[10:11]
	s_waitcnt lgkmcnt(5)
	v_cvt_pk_bf16_f32 v2, v154, v155
	s_waitcnt lgkmcnt(4)
	v_cvt_pk_bf16_f32 v3, v156, v157
	global_store_dwordx4 v[10:11], v[0:3], off
	v_add_u32_e32 v10, 40, v4
	v_ashrrev_i32_e32 v11, 31, v10
	s_waitcnt lgkmcnt(3)
	v_cvt_pk_bf16_f32 v0, v158, v159
	v_lshlrev_b64 v[10:11], 11, v[10:11]
	s_waitcnt lgkmcnt(2)
	v_cvt_pk_bf16_f32 v1, v160, v161
	v_lshl_add_u64 v[10:11], v[6:7], 0, v[10:11]
	s_waitcnt lgkmcnt(1)
	v_cvt_pk_bf16_f32 v2, v162, v163
	s_waitcnt lgkmcnt(0)
	v_cvt_pk_bf16_f32 v3, v164, v165
	global_store_dwordx4 v[10:11], v[0:3], off
	v_add_u32_e32 v10, 48, v4
	ds_read2_b32 v[150:151], v85 offset0:48 offset1:113
	ds_read2_b32 v[152:153], v85 offset0:178 offset1:243
	ds_read2_b32 v[154:155], v12 offset0:52 offset1:117
	ds_read2_b32 v[156:157], v12 offset0:182 offset1:247
	ds_read2_b32 v[158:159], v85 offset0:56 offset1:121
	ds_read2_b32 v[160:161], v85 offset0:186 offset1:251
	ds_read2_b32 v[162:163], v12 offset0:60 offset1:125
	ds_read2_b32 v[164:165], v12 offset0:190 offset1:255
	s_waitcnt lgkmcnt(7)
	v_cvt_pk_bf16_f32 v0, v150, v151
	v_ashrrev_i32_e32 v11, 31, v10
	s_waitcnt lgkmcnt(6)
	v_cvt_pk_bf16_f32 v1, v152, v153
	v_lshlrev_b64 v[10:11], 11, v[10:11]
	v_add_u32_e32 v4, 56, v4
	s_waitcnt lgkmcnt(5)
	v_cvt_pk_bf16_f32 v2, v154, v155
	s_waitcnt lgkmcnt(4)
	v_cvt_pk_bf16_f32 v3, v156, v157
	v_lshl_add_u64 v[10:11], v[6:7], 0, v[10:11]
	v_ashrrev_i32_e32 v5, 31, v4
	global_store_dwordx4 v[10:11], v[0:3], off
	v_lshlrev_b64 v[4:5], 11, v[4:5]
	v_lshl_add_u64 v[4:5], v[6:7], 0, v[4:5]
	s_waitcnt lgkmcnt(3)
	v_cvt_pk_bf16_f32 v0, v158, v159
	s_waitcnt lgkmcnt(2)
	v_cvt_pk_bf16_f32 v1, v160, v161
	s_waitcnt lgkmcnt(1)
	v_cvt_pk_bf16_f32 v2, v162, v163
	s_waitcnt lgkmcnt(0)
	v_cvt_pk_bf16_f32 v3, v164, v165
	global_store_dwordx4 v[4:5], v[0:3], off
	s_waitcnt lgkmcnt(0)
	s_branch .LBB0_163
